# lever 4, other half: static s_setprio 1 for waves 0..3 in the diff and stick-breaking units
# speedup vs baseline: 1.0030x; 1.0006x over previous
.Lmx_sb_go:
	v_readfirstlane_b32 s98, v214
	s_cmpk_lt_u32 s98, 0x100
	s_cbranch_scc0 .Lprio_sb
	s_setprio 1
